# waves 0-3 issue all LDS-DMA of the GEMM1/GEMM3 k-loops (own and SIMD partner pieces) and run at static s_setprio 1
# speedup vs baseline: 1.0051x; 1.0045x over previous
; __device__ __forceinline__ int opaque_tid() { int t = threadIdx.x; asm volatile("" : "+v"(t)); return t; }
; __device__ void phase0(const Params& P, char* smem) {
;   const int tid = opaque_tid();
;   float* tile = (float*)smem;
;   const int n0_ = 4 * 16 * 141, n1_ = 4 * 16 * 16, n2_ = 4 * 32 * 2, n3_ = 4 * 2 * 1;
;   const int nT = n0_ + 3 * n1_ + 2 * n2_ + 2 * n3_;
;   const int nBias = 64, nRope = 128;
;   const int total = nT + nBias + nRope + 1;
;   for (int it = blockIdx.x; it < total; it += gridDim.x) {
;     if (it < nT) {
;       int t = it;
;       if (t < n0_) {
;         int l = t / (16 * 141), rem = t % (16 * 141);
; __global__ void __launch_bounds__(NTHREADS, 2) mega_kernel(Params P) {
;   __shared__ __attribute__((aligned(1024))) char smem[163840];
;   cg::grid_group grid = cg::this_grid();
;   const int CT = P.NB * TSEQ;
;   phase0(P, smem);
_Z11mega_kernel6Params:
	v_readfirstlane_b32 s32, v0
	s_bitcmp1_b32 s32, 8
	s_cbranch_scc1 .Lmy_noprio
	s_setprio 1
.Lmy_noprio:
	s_load_dword s33, s[0:1], 0x138
	s_mov_b64 s[60:61], s[0:1]
	s_mov_b32 s97, s2
	s_add_u32 s2, s60, 0x138
	s_addc_u32 s3, s61, 0
	v_and_b32_e32 v195, 0x3ff, v0
	s_movk_i32 s62, 0x3ff
	v_mov_b32_e32 v2, v195
	s_cmpk_gt_i32 s97, 0x3210
	s_cbranch_scc1 .LBB0_48
	v_ashrrev_i32_e32 v6, 3, v2
	v_lshlrev_b32_e32 v7, 3, v2
	s_movk_i32 s8, 0x104
	v_and_b32_e32 v18, 56, v7
	v_lshlrev_b32_e32 v7, 2, v6
	s_load_dwordx2 s[30:31], s[60:61], 0xb8
	s_load_dwordx4 s[24:27], s[60:61], 0x120
	s_load_dwordx8 s[16:23], s[60:61], 0x98
	v_mad_u32_u24 v38, v18, s8, v7
	v_ashrrev_i32_e32 v7, 31, v6
	v_lshlrev_b64 v[10:11], 8, v[6:7]
	v_max_i32_e32 v7, 0xa80, v2
	v_sub_u32_e32 v7, v7, v2
	v_add_u32_e32 v7, 0x1ff, v7
	v_ashrrev_i32_e32 v4, 1, v2
	v_lshlrev_b32_e32 v35, 2, v2
	v_ashrrev_i32_e32 v36, 4, v2
	s_waitcnt lgkmcnt(0)
	v_mov_b32_e32 v8, s24
	v_mov_b32_e32 v9, s25
	v_lshl_add_u64 v[10:11], s[18:19], 0, v[10:11]
	s_load_dwordx2 s[18:19], s[60:61], 0x10
	s_load_dwordx2 s[24:25], s[60:61], 0x78
	v_lshrrev_b32_e32 v12, 9, v7
	v_and_b32_e32 v34, 0xffffffc0, v4
	v_and_b32_e32 v4, 60, v35
	v_mul_lo_u32 v20, v36, s8
	s_movk_i32 s8, 0x1ff
	v_add_u32_e32 v13, 1, v12
	s_movk_i32 s4, 0x100
	v_lshlrev_b32_e32 v19, 2, v4
	v_cmp_lt_u32_e64 s[8:9], s8, v7
	v_and_b32_e32 v7, 0xfffffe, v13
	v_and_b32_e32 v32, 31, v2
	v_cmp_gt_i32_e64 s[12:13], s4, v2
	v_ashrrev_i32_e32 v3, 31, v2
	s_movk_i32 s4, 0xc80
	v_and_b32_e32 v33, 0x7f, v2
	s_movk_i32 s6, 0x80
	v_mov_b32_e32 v5, 0
	v_lshl_add_u32 v12, v7, 9, v2
	v_cmp_ne_u32_e64 s[10:11], v13, v7
	v_mov_b32_e32 v13, 0x800
	s_mov_b32 s34, 0x24115d99
	s_mov_b32 s36, 0x6dc9c883
	s_mov_b32 s38, 0x54442d18
	v_add_u32_e32 v39, v19, v20
	v_add_u32_e32 v1, 0xff9ce000, v2
	s_mov_b32 s29, 0
	v_cmp_ne_u32_e64 s[0:1], 0, v32
	v_cmp_gt_i32_e64 s[4:5], s4, v2
	v_cmp_gt_i32_e64 s[6:7], s6, v2
	v_add_u32_e32 v37, 32, v36
	v_lshl_add_u64 v[8:9], v[2:3], 2, v[8:9]
	v_add_u32_e32 v15, 0x200, v2
	v_mov_b32_e32 v14, v2
	s_add_i32 s50, s97, 0xffffceb0
	v_lshl_or_b32 v16, v33, 2, v13
	v_mov_b32_e32 v17, v5
	s_mov_b32 s35, 0x3fe7ff22
	s_mov_b32 s37, 0x3fc45f30
	s_mov_b32 s39, 0xc01921fb
	v_ashrrev_i32_e32 v13, 31, v12
	s_mov_b64 s[40:41], 0x800
	s_movk_i32 s51, 0xa7f
	s_mov_b64 s[42:43], 0x1000
	v_add_u32_e32 v40, 0x2080, v39
	v_add_u32_e32 v41, 0x2088, v39
	s_movk_i32 s52, 0x58
	s_movk_i32 s53, 0x88
	s_mov_b32 s54, 0x8d00
	v_lshlrev_b32_e32 v4, 2, v4
	v_add_u32_e32 v42, 0x400, v38
	v_lshlrev_b32_e32 v18, 1, v18
	s_mov_b32 s55, s97
	s_mov_b32 s56, s97
	s_branch .LBB0_3

; #define G_WAIT_V0() asm volatile("s_waitcnt vmcnt(0)" ::: "memory")
; __device__ __forceinline__ void g_kloop(const u16* __restrict__ Ab, const u16* __restrict__ Bb, const int K, char* smem, ...
;     ...
;   const int nt = K >> 6;
;   if (!pre) {
;     G_STAGE(0, 0);
;     G_WAIT_V0();
;     __syncthreads();
;   }
;   for (int t = 0; t < nt; ++t) {
;     const int cur = t & 1;
;     if (t + 1 < nt) G_STAGE(cur ^ 1, t + 1)
;     else if (has_next) {
;       char* sa_ = smem + wid * 1024;
;       char* sb_ = sa_ + G_TILE_B;
;       __builtin_amdgcn_global_load_lds((const unsigned*)(nA + o0), (unsigned*)(sa_), 16, 0, 0);
;       __builtin_amdgcn_global_load_lds((const unsigned*)(nB + o0), (unsigned*)(sb_), 16, 0, 0);
;       __builtin_amdgcn_global_load_lds((const unsigned*)(nA + o1), (unsigned*)(sa_ + 8192), 16, 0, 0);
;       __builtin_amdgcn_global_load_lds((const unsigned*)(nB + o1), (unsigned*)(sb_ + 8192), 16, 0, 0);
;       __builtin_amdgcn_global_load_lds((const unsigned*)(nA + o2), (unsigned*)(sa_ + 16384), 16, 0, 0);
;       __builtin_amdgcn_global_load_lds((const unsigned*)(nB + o2), (unsigned*)(sb_ + 16384), 16, 0, 0);
;       __builtin_amdgcn_global_load_lds((const unsigned*)(nA + o3), (unsigned*)(sa_ + 24576), 16, 0, 0);
;       __builtin_amdgcn_global_load_lds((const unsigned*)(nB + o3), (unsigned*)(sb_ + 24576), 16, 0, 0);
;     }
;     const char* sa = smem + cur * G_STAGE_B;
;     const char* sb = sa + G_TILE_B;
; #pragma unroll
;     for (int ks = 0; ks < 2; ++ks) {
;       s16x8 At[8], Bf[4];
; #pragma unroll
;       for (int m = 0; m < 8; ++m) At[m] = *(const s16x8*)(sa + g_lds_byte(wr * 128 + m * 16 + fr, ks * 32 + fq * 8));
; #pragma unroll
;       for (int n = 0; n < 4; ++n) Bf[n] = *(const s16x8*)(sb + g_lds_byte(wc * 64 + n * 16 + fr, ks * 32 + fq * 8));
; #pragma unroll
;       for (int m = 0; m < 8; ++m)
; #pragma unroll
;         for (int n = 0; n < 4; ++n)
;           acc[m][n] = __builtin_amdgcn_mfma_f32_16x16x32_bf16(__builtin_bit_cast(bf16x8, Bf[n]), __builtin_bit_cast(bf16x8, At[m]), acc[m][n], 0, 0, 0);
;     }
;     G_WAIT_V0();
;     __syncthreads();
;   }
.LBB0_119:
	v_readfirstlane_b32 s32, v166
	s_cmp_ge_u32 s32, 0x1000
	s_cselect_b64 vcc, -1, 0
	s_and_b32 s14, s1, 0x10000
	v_or_b32_e32 v96, s14, v170
	v_add_u32_e32 v182, v96, v171
	v_add_u32_e32 v96, v96, v172
	ds_read_b128 v[130:133], v96 offset:32768
	ds_read_b128 v[138:141], v96 offset:34816
	ds_read_b128 v[174:177], v96 offset:36864
	ds_read_b128 v[178:181], v96 offset:38912
	ds_read_b128 v[134:137], v182
	ds_read_b128 v[204:207], v182 offset:2048
	ds_read_b128 v[208:211], v182 offset:4096
	ds_read_b128 v[212:215], v182 offset:6144
.Lmy_k1_top:
	s_and_b32 s5, s1, 0x10000
	s_xor_b32 s14, s5, 0x10000
	v_add_u32_e32 v252, s14, v166
	s_waitcnt lgkmcnt(3)
	v_mfma_f32_16x16x32_bf16 v[4:7], v[130:133], v[134:137], v[4:7]
	v_mfma_f32_16x16x32_bf16 v[114:117], v[138:141], v[134:137], v[114:117]
	v_mfma_f32_16x16x32_bf16 v[110:113], v[174:177], v[134:137], v[110:113]
	v_mfma_f32_16x16x32_bf16 v[106:109], v[178:181], v[134:137], v[106:109]
	ds_read_b128 v[134:137], v182 offset:8192
	v_readfirstlane_b32 s5, v252
	s_add_u32 s100, s12, 0x10000
	s_addc_u32 s101, s13, 0
	s_cbranch_vccnz .Lmy_k1_d1
	s_mov_b32 m0, s5
	v_lshl_add_u64 v[220:221], v[150:151], 0, s[12:13]
	global_load_lds_dwordx4 v[220:221], off
	s_add_u32 m0, s5, 0x1000
	v_lshl_add_u64 v[220:221], v[150:151], 0, s[100:101]
	global_load_lds_dwordx4 v[220:221], off
.Lmy_k1_d1:
	s_waitcnt lgkmcnt(3)
	v_mfma_f32_16x16x32_bf16 v[102:105], v[130:133], v[204:207], v[102:105]
	v_mfma_f32_16x16x32_bf16 v[92:95], v[138:141], v[204:207], v[92:95]
	v_mfma_f32_16x16x32_bf16 v[76:79], v[174:177], v[204:207], v[76:79]
	v_mfma_f32_16x16x32_bf16 v[48:51], v[178:181], v[204:207], v[48:51]
	ds_read_b128 v[204:207], v182 offset:10240
	s_cbranch_vccnz .Lmy_k1_d2
	s_add_u32 m0, s5, 0x8000
	v_lshl_add_u64 v[220:221], v[158:159], 0, s[12:13]
	global_load_lds_dwordx4 v[220:221], off
	s_add_u32 m0, s5, 0x9000
	v_lshl_add_u64 v[220:221], v[158:159], 0, s[100:101]
	global_load_lds_dwordx4 v[220:221], off
.Lmy_k1_d2:
	s_waitcnt lgkmcnt(3)
	v_mfma_f32_16x16x32_bf16 v[98:101], v[130:133], v[208:211], v[98:101]
	v_mfma_f32_16x16x32_bf16 v[84:87], v[138:141], v[208:211], v[84:87]
	v_mfma_f32_16x16x32_bf16 v[64:67], v[174:177], v[208:211], v[64:67]
	v_mfma_f32_16x16x32_bf16 v[36:39], v[178:181], v[208:211], v[36:39]
	ds_read_b128 v[208:211], v182 offset:12288
	ds_read_b128 v[216:219], v96 offset:33792
	s_cbranch_vccnz .Lmy_k1_d3
	s_add_u32 m0, s5, 0x2000
	v_lshl_add_u64 v[220:221], v[152:153], 0, s[12:13]
	global_load_lds_dwordx4 v[220:221], off
	s_add_u32 m0, s5, 0x3000
	v_lshl_add_u64 v[220:221], v[152:153], 0, s[100:101]
	global_load_lds_dwordx4 v[220:221], off
.Lmy_k1_d3:
	s_waitcnt lgkmcnt(4)
	v_mfma_f32_16x16x32_bf16 v[88:91], v[130:133], v[212:215], v[88:91]
	v_mfma_f32_16x16x32_bf16 v[72:75], v[138:141], v[212:215], v[72:75]
	v_mfma_f32_16x16x32_bf16 v[52:55], v[174:177], v[212:215], v[52:55]
	v_mfma_f32_16x16x32_bf16 v[24:27], v[178:181], v[212:215], v[24:27]
	ds_read_b128 v[212:215], v182 offset:14336
	ds_read_b128 v[230:233], v96 offset:35840
	s_cbranch_vccnz .Lmy_k1_d4
	s_add_u32 m0, s5, 0xa000
	v_lshl_add_u64 v[220:221], v[160:161], 0, s[12:13]
	global_load_lds_dwordx4 v[220:221], off
	s_add_u32 m0, s5, 0xb000
	v_lshl_add_u64 v[220:221], v[160:161], 0, s[100:101]
	global_load_lds_dwordx4 v[220:221], off
.Lmy_k1_d4:
	s_waitcnt lgkmcnt(5)
	v_mfma_f32_16x16x32_bf16 v[80:83], v[130:133], v[134:137], v[80:83]
	v_mfma_f32_16x16x32_bf16 v[60:63], v[138:141], v[134:137], v[60:63]
	v_mfma_f32_16x16x32_bf16 v[40:43], v[174:177], v[134:137], v[40:43]
	v_mfma_f32_16x16x32_bf16 v[16:19], v[178:181], v[134:137], v[16:19]
	ds_read_b128 v[134:137], v182 offset:1024
	ds_read_b128 v[244:247], v96 offset:37888
	s_cbranch_vccnz .Lmy_k1_d5
	s_add_u32 m0, s5, 0x4000
	v_lshl_add_u64 v[220:221], v[154:155], 0, s[12:13]
	global_load_lds_dwordx4 v[220:221], off
	s_add_u32 m0, s5, 0x5000
	v_lshl_add_u64 v[220:221], v[154:155], 0, s[100:101]
	global_load_lds_dwordx4 v[220:221], off
.Lmy_k1_d5:
	s_waitcnt lgkmcnt(6)
	v_mfma_f32_16x16x32_bf16 v[68:71], v[130:133], v[204:207], v[68:71]
	v_mfma_f32_16x16x32_bf16 v[44:47], v[138:141], v[204:207], v[44:47]
	v_mfma_f32_16x16x32_bf16 v[28:31], v[174:177], v[204:207], v[28:31]
	v_mfma_f32_16x16x32_bf16 v[12:15], v[178:181], v[204:207], v[12:15]
	ds_read_b128 v[204:207], v182 offset:3072
	ds_read_b128 v[248:251], v96 offset:39936
	s_cbranch_vccnz .Lmy_k1_d6
	s_add_u32 m0, s5, 0xc000
	v_lshl_add_u64 v[220:221], v[162:163], 0, s[12:13]
	global_load_lds_dwordx4 v[220:221], off
	s_add_u32 m0, s5, 0xd000
	v_lshl_add_u64 v[220:221], v[162:163], 0, s[100:101]
	global_load_lds_dwordx4 v[220:221], off
.Lmy_k1_d6:
	s_waitcnt lgkmcnt(7)
	v_mfma_f32_16x16x32_bf16 v[56:59], v[130:133], v[208:211], v[56:59]
	v_mfma_f32_16x16x32_bf16 v[32:35], v[138:141], v[208:211], v[32:35]
	v_mfma_f32_16x16x32_bf16 v[20:23], v[174:177], v[208:211], v[20:23]
	v_mfma_f32_16x16x32_bf16 v[8:11], v[178:181], v[208:211], v[8:11]
	ds_read_b128 v[208:211], v182 offset:5120
	s_cbranch_vccnz .Lmy_k1_d7
	s_add_u32 m0, s5, 0x6000
	v_lshl_add_u64 v[220:221], v[156:157], 0, s[12:13]
	global_load_lds_dwordx4 v[220:221], off
	s_add_u32 m0, s5, 0x7000
	v_lshl_add_u64 v[220:221], v[156:157], 0, s[100:101]
	global_load_lds_dwordx4 v[220:221], off
; #define G_WAIT_V0() asm volatile("s_waitcnt vmcnt(0)" ::: "memory")
; __device__ __forceinline__ void g_kloop(const u16* __restrict__ Ab, const u16* __restrict__ Bb, const int K, char* smem, ...
;     ...
;   const int nt = K >> 6;
;   if (!pre) {
;     G_STAGE(0, 0);
;     G_WAIT_V0();
;     __syncthreads();
;   }
;   for (int t = 0; t < nt; ++t) {
;     const int cur = t & 1;
;     if (t + 1 < nt) G_STAGE(cur ^ 1, t + 1)
;     else if (has_next) {
;       char* sa_ = smem + wid * 1024;
;       char* sb_ = sa_ + G_TILE_B;
;       __builtin_amdgcn_global_load_lds((const unsigned*)(nA + o0), (unsigned*)(sa_), 16, 0, 0);
;       __builtin_amdgcn_global_load_lds((const unsigned*)(nB + o0), (unsigned*)(sb_), 16, 0, 0);
;       __builtin_amdgcn_global_load_lds((const unsigned*)(nA + o1), (unsigned*)(sa_ + 8192), 16, 0, 0);
;       __builtin_amdgcn_global_load_lds((const unsigned*)(nB + o1), (unsigned*)(sb_ + 8192), 16, 0, 0);
;       __builtin_amdgcn_global_load_lds((const unsigned*)(nA + o2), (unsigned*)(sa_ + 16384), 16, 0, 0);
;       __builtin_amdgcn_global_load_lds((const unsigned*)(nB + o2), (unsigned*)(sb_ + 16384), 16, 0, 0);
;       __builtin_amdgcn_global_load_lds((const unsigned*)(nA + o3), (unsigned*)(sa_ + 24576), 16, 0, 0);
;       __builtin_amdgcn_global_load_lds((const unsigned*)(nB + o3), (unsigned*)(sb_ + 24576), 16, 0, 0);
;     }
;     const char* sa = smem + cur * G_STAGE_B;
;     const char* sb = sa + G_TILE_B;
; #pragma unroll
;     for (int ks = 0; ks < 2; ++ks) {
;       s16x8 At[8], Bf[4];
; #pragma unroll
;       for (int m = 0; m < 8; ++m) At[m] = *(const s16x8*)(sa + g_lds_byte(wr * 128 + m * 16 + fr, ks * 32 + fq * 8));
; #pragma unroll
;       for (int n = 0; n < 4; ++n) Bf[n] = *(const s16x8*)(sb + g_lds_byte(wc * 64 + n * 16 + fr, ks * 32 + fq * 8));
; #pragma unroll
;       for (int m = 0; m < 8; ++m)
; #pragma unroll
;         for (int n = 0; n < 4; ++n)
;           acc[m][n] = __builtin_amdgcn_mfma_f32_16x16x32_bf16(__builtin_bit_cast(bf16x8, Bf[n]), __builtin_bit_cast(bf16x8, At[m]), acc[m][n], 0, 0, 0);
;     }
;     G_WAIT_V0();
;     __syncthreads();
;   }
.Lmy_k1_d7:
	s_waitcnt lgkmcnt(6)
	v_mfma_f32_16x16x32_bf16 v[122:125], v[130:133], v[212:215], v[122:125]
	v_mfma_f32_16x16x32_bf16 v[118:121], v[138:141], v[212:215], v[118:121]
	v_mfma_f32_16x16x32_bf16 v[126:129], v[174:177], v[212:215], v[126:129]
	v_mfma_f32_16x16x32_bf16 v[0:3], v[178:181], v[212:215], v[0:3]
	ds_read_b128 v[212:215], v182 offset:7168
	s_cbranch_vccnz .Lmy_k1_d8
	s_add_u32 m0, s5, 0xe000
	v_lshl_add_u64 v[220:221], v[164:165], 0, s[12:13]
	global_load_lds_dwordx4 v[220:221], off
	s_add_u32 m0, s5, 0xf000
	v_lshl_add_u64 v[220:221], v[164:165], 0, s[100:101]
	global_load_lds_dwordx4 v[220:221], off
.Lmy_k1_d8:
	s_waitcnt lgkmcnt(5)
	v_mfma_f32_16x16x32_bf16 v[4:7], v[216:219], v[134:137], v[4:7]
	v_mfma_f32_16x16x32_bf16 v[114:117], v[230:233], v[134:137], v[114:117]
	s_waitcnt lgkmcnt(4)
	v_mfma_f32_16x16x32_bf16 v[110:113], v[244:247], v[134:137], v[110:113]
	s_waitcnt lgkmcnt(2)
	v_mfma_f32_16x16x32_bf16 v[106:109], v[248:251], v[134:137], v[106:109]
	ds_read_b128 v[134:137], v182 offset:9216
	v_mfma_f32_16x16x32_bf16 v[102:105], v[216:219], v[204:207], v[102:105]
	v_mfma_f32_16x16x32_bf16 v[92:95], v[230:233], v[204:207], v[92:95]
	v_mfma_f32_16x16x32_bf16 v[76:79], v[244:247], v[204:207], v[76:79]
	v_mfma_f32_16x16x32_bf16 v[48:51], v[248:251], v[204:207], v[48:51]
	ds_read_b128 v[204:207], v182 offset:11264
	s_waitcnt lgkmcnt(3)
	v_mfma_f32_16x16x32_bf16 v[98:101], v[216:219], v[208:211], v[98:101]
	v_mfma_f32_16x16x32_bf16 v[84:87], v[230:233], v[208:211], v[84:87]
	v_mfma_f32_16x16x32_bf16 v[64:67], v[244:247], v[208:211], v[64:67]
	v_mfma_f32_16x16x32_bf16 v[36:39], v[248:251], v[208:211], v[36:39]
	ds_read_b128 v[208:211], v182 offset:13312
	s_waitcnt lgkmcnt(3)
	v_mfma_f32_16x16x32_bf16 v[88:91], v[216:219], v[212:215], v[88:91]
	v_mfma_f32_16x16x32_bf16 v[72:75], v[230:233], v[212:215], v[72:75]
	v_mfma_f32_16x16x32_bf16 v[52:55], v[244:247], v[212:215], v[52:55]
	v_mfma_f32_16x16x32_bf16 v[24:27], v[248:251], v[212:215], v[24:27]
	ds_read_b128 v[212:215], v182 offset:15360
	s_waitcnt lgkmcnt(3)
	v_mfma_f32_16x16x32_bf16 v[80:83], v[216:219], v[134:137], v[80:83]
	v_mfma_f32_16x16x32_bf16 v[60:63], v[230:233], v[134:137], v[60:63]
	v_mfma_f32_16x16x32_bf16 v[40:43], v[244:247], v[134:137], v[40:43]
	v_mfma_f32_16x16x32_bf16 v[16:19], v[248:251], v[134:137], v[16:19]
	s_waitcnt lgkmcnt(2)
	v_mfma_f32_16x16x32_bf16 v[68:71], v[216:219], v[204:207], v[68:71]
	v_mfma_f32_16x16x32_bf16 v[44:47], v[230:233], v[204:207], v[44:47]
	v_mfma_f32_16x16x32_bf16 v[28:31], v[244:247], v[204:207], v[28:31]
	v_mfma_f32_16x16x32_bf16 v[12:15], v[248:251], v[204:207], v[12:15]
	s_waitcnt vmcnt(0)
	s_waitcnt vmcnt(0) lgkmcnt(0)
	s_barrier
	s_add_i32 s1, s1, 0x10000
	s_add_u32 s12, s12, 0x80
	s_addc_u32 s13, s13, 0
	s_and_b32 s14, s1, 0x10000
	v_or_b32_e32 v96, s14, v170
	v_add_u32_e32 v182, v96, v171
	v_add_u32_e32 v96, v96, v172
	ds_read_b128 v[130:133], v96 offset:32768
	ds_read_b128 v[138:141], v96 offset:34816
	ds_read_b128 v[174:177], v96 offset:36864
	ds_read_b128 v[178:181], v96 offset:38912
	ds_read_b128 v[134:137], v182
	ds_read_b128 v[204:207], v182 offset:2048
	v_mfma_f32_16x16x32_bf16 v[56:59], v[216:219], v[208:211], v[56:59]
	v_mfma_f32_16x16x32_bf16 v[32:35], v[230:233], v[208:211], v[32:35]
	v_mfma_f32_16x16x32_bf16 v[20:23], v[244:247], v[208:211], v[20:23]
	v_mfma_f32_16x16x32_bf16 v[8:11], v[248:251], v[208:211], v[8:11]
	ds_read_b128 v[208:211], v182 offset:4096
	v_mfma_f32_16x16x32_bf16 v[122:125], v[216:219], v[212:215], v[122:125]
	v_mfma_f32_16x16x32_bf16 v[118:121], v[230:233], v[212:215], v[118:121]
	v_mfma_f32_16x16x32_bf16 v[126:129], v[244:247], v[212:215], v[126:129]
	v_mfma_f32_16x16x32_bf16 v[0:3], v[248:251], v[212:215], v[0:3]
	ds_read_b128 v[212:215], v182 offset:6144
	s_cmpk_lg_i32 s12, 0x780
	s_cbranch_scc1 .Lmy_k1_top
	s_waitcnt lgkmcnt(0)
	s_andn2_b64 vcc, exec, s[10:11]
	s_cbranch_vccnz .LBB0_122
	s_lshl_b32 s10, s25, 8
	s_ashr_i32 s11, s10, 31
	s_lshl_b64 s[10:11], s[10:11], 11
	s_add_u32 s10, s86, s10
	s_addc_u32 s11, s87, s11
	s_lshl_b32 s12, s24, 8
	s_ashr_i32 s13, s12, 31
	s_lshl_b64 s[12:13], s[12:13], 11
	s_add_u32 s12, s20, s12
	v_lshlrev_b64 v[130:131], 1, v[142:143]
	v_add_u32_e32 v151, 0x8000, v166
	v_readfirstlane_b32 s1, v166
	s_addc_u32 s13, s21, s13
	v_lshl_add_u64 v[132:133], s[10:11], 0, v[130:131]
	v_add_u32_e32 v150, 0x2000, v166
	s_mov_b32 m0, s1
	v_readfirstlane_b32 s1, v151
	v_lshl_add_u64 v[130:131], s[12:13], 0, v[130:131]
	v_lshlrev_b64 v[134:135], 1, v[144:145]
	v_lshlrev_b64 v[142:143], 1, v[148:149]
	v_add_u32_e32 v149, 0xa000, v166
	global_load_lds_dwordx4 v[132:133], off
	s_mov_b32 m0, s1
	v_readfirstlane_b32 s1, v150
	v_lshl_add_u64 v[136:137], s[10:11], 0, v[134:135]
	v_add_u32_e32 v148, 0x4000, v166
	global_load_lds_dwordx4 v[130:131], off
	s_mov_b32 m0, s1
	v_readfirstlane_b32 s1, v149
	v_lshl_add_u64 v[134:135], s[12:13], 0, v[134:135]
	v_lshlrev_b64 v[138:139], 1, v[146:147]
	v_add_u32_e32 v147, 0xc000, v166
	global_load_lds_dwordx4 v[136:137], off
	s_mov_b32 m0, s1
	v_readfirstlane_b32 s1, v148
	v_lshl_add_u64 v[140:141], s[10:11], 0, v[138:139]
	v_add_u32_e32 v146, 0x6000, v166
	global_load_lds_dwordx4 v[134:135], off
	s_mov_b32 m0, s1
	v_readfirstlane_b32 s1, v147
	v_lshl_add_u64 v[138:139], s[12:13], 0, v[138:139]
	v_add_u32_e32 v96, 0xe000, v166
	global_load_lds_dwordx4 v[140:141], off
	s_mov_b32 m0, s1
	v_readfirstlane_b32 s1, v146
	v_lshl_add_u64 v[144:145], s[10:11], 0, v[142:143]
	global_load_lds_dwordx4 v[138:139], off
	s_mov_b32 m0, s1
	v_readfirstlane_b32 s1, v96
	v_lshl_add_u64 v[142:143], s[12:13], 0, v[142:143]
	global_load_lds_dwordx4 v[144:145], off
	s_mov_b32 m0, s1
	s_nop 0
	global_load_lds_dwordx4 v[142:143], off

; #define G_WAIT_V0() asm volatile("s_waitcnt vmcnt(0)" ::: "memory")
; __device__ __forceinline__ void g_kloop(const u16* __restrict__ Ab, const u16* __restrict__ Bb, const int K, char* smem, ...
;     ...
;   const int nt = K >> 6;
;   if (!pre) {
;     G_STAGE(0, 0);
;     G_WAIT_V0();
;     __syncthreads();
;   }
;   for (int t = 0; t < nt; ++t) {
;     const int cur = t & 1;
;     if (t + 1 < nt) G_STAGE(cur ^ 1, t + 1)
;     else if (has_next) {
;       char* sa_ = smem + wid * 1024;
;       char* sb_ = sa_ + G_TILE_B;
;       __builtin_amdgcn_global_load_lds((const unsigned*)(nA + o0), (unsigned*)(sa_), 16, 0, 0);
;       __builtin_amdgcn_global_load_lds((const unsigned*)(nB + o0), (unsigned*)(sb_), 16, 0, 0);
;       __builtin_amdgcn_global_load_lds((const unsigned*)(nA + o1), (unsigned*)(sa_ + 8192), 16, 0, 0);
;       __builtin_amdgcn_global_load_lds((const unsigned*)(nB + o1), (unsigned*)(sb_ + 8192), 16, 0, 0);
;       __builtin_amdgcn_global_load_lds((const unsigned*)(nA + o2), (unsigned*)(sa_ + 16384), 16, 0, 0);
;       __builtin_amdgcn_global_load_lds((const unsigned*)(nB + o2), (unsigned*)(sb_ + 16384), 16, 0, 0);
;       __builtin_amdgcn_global_load_lds((const unsigned*)(nA + o3), (unsigned*)(sa_ + 24576), 16, 0, 0);
;       __builtin_amdgcn_global_load_lds((const unsigned*)(nB + o3), (unsigned*)(sb_ + 24576), 16, 0, 0);
;     }
;     const char* sa = smem + cur * G_STAGE_B;
;     const char* sb = sa + G_TILE_B;
; #pragma unroll
;     for (int ks = 0; ks < 2; ++ks) {
;       s16x8 At[8], Bf[4];
; #pragma unroll
;       for (int m = 0; m < 8; ++m) At[m] = *(const s16x8*)(sa + g_lds_byte(wr * 128 + m * 16 + fr, ks * 32 + fq * 8));
; #pragma unroll
;       for (int n = 0; n < 4; ++n) Bf[n] = *(const s16x8*)(sb + g_lds_byte(wc * 64 + n * 16 + fr, ks * 32 + fq * 8));
; #pragma unroll
;       for (int m = 0; m < 8; ++m)
; #pragma unroll
;         for (int n = 0; n < 4; ++n)
;           acc[m][n] = __builtin_amdgcn_mfma_f32_16x16x32_bf16(__builtin_bit_cast(bf16x8, Bf[n]), __builtin_bit_cast(bf16x8, At[m]), acc[m][n], 0, 0, 0);
;     }
;     G_WAIT_V0();
;     __syncthreads();
;   }
.LBB0_631:
	v_readfirstlane_b32 s32, v166
	s_cmp_ge_u32 s32, 0x1000
	s_cselect_b64 vcc, -1, 0
	s_and_b32 s13, s7, 0x10000
	v_or_b32_e32 v96, s13, v179
	v_add_u32_e32 v191, v96, v180
	v_add_u32_e32 v96, v96, v181
	ds_read_b128 v[130:133], v96 offset:32768
	ds_read_b128 v[138:141], v96 offset:34816
	ds_read_b128 v[182:185], v96 offset:36864
	ds_read_b128 v[186:189], v96 offset:38912
	ds_read_b128 v[134:137], v191
	ds_read_b128 v[204:207], v191 offset:2048
	ds_read_b128 v[208:211], v191 offset:4096
	ds_read_b128 v[212:215], v191 offset:6144
.Lmy_k3_top:
	s_and_b32 s12, s7, 0x10000
	s_xor_b32 s13, s12, 0x10000
	v_add_u32_e32 v252, s13, v166
	s_waitcnt lgkmcnt(3)
	v_mfma_f32_16x16x32_bf16 v[4:7], v[130:133], v[134:137], v[4:7]
	v_mfma_f32_16x16x32_bf16 v[114:117], v[138:141], v[134:137], v[114:117]
	v_mfma_f32_16x16x32_bf16 v[110:113], v[182:185], v[134:137], v[110:113]
	v_mfma_f32_16x16x32_bf16 v[106:109], v[186:189], v[134:137], v[106:109]
	ds_read_b128 v[134:137], v191 offset:8192
	v_readfirstlane_b32 s12, v252
	s_add_u32 s100, s10, 0x10000
	s_addc_u32 s101, s11, 0
	s_cbranch_vccnz .Lmy_k3_d1
	s_mov_b32 m0, s12
	v_lshl_add_u64 v[220:221], v[150:151], 0, s[10:11]
	global_load_lds_dwordx4 v[220:221], off
	s_add_u32 m0, s12, 0x1000
	v_lshl_add_u64 v[220:221], v[150:151], 0, s[100:101]
	global_load_lds_dwordx4 v[220:221], off
.Lmy_k3_d1:
	s_waitcnt lgkmcnt(3)
	v_mfma_f32_16x16x32_bf16 v[102:105], v[130:133], v[204:207], v[102:105]
	v_mfma_f32_16x16x32_bf16 v[92:95], v[138:141], v[204:207], v[92:95]
	v_mfma_f32_16x16x32_bf16 v[76:79], v[182:185], v[204:207], v[76:79]
	v_mfma_f32_16x16x32_bf16 v[48:51], v[186:189], v[204:207], v[48:51]
	ds_read_b128 v[204:207], v191 offset:10240
	s_cbranch_vccnz .Lmy_k3_d2
	s_add_u32 m0, s12, 0x8000
	v_lshl_add_u64 v[220:221], v[158:159], 0, s[10:11]
	global_load_lds_dwordx4 v[220:221], off
	s_add_u32 m0, s12, 0x9000
	v_lshl_add_u64 v[220:221], v[158:159], 0, s[100:101]
	global_load_lds_dwordx4 v[220:221], off
.Lmy_k3_d2:
	s_waitcnt lgkmcnt(3)
	v_mfma_f32_16x16x32_bf16 v[98:101], v[130:133], v[208:211], v[98:101]
	v_mfma_f32_16x16x32_bf16 v[84:87], v[138:141], v[208:211], v[84:87]
	v_mfma_f32_16x16x32_bf16 v[64:67], v[182:185], v[208:211], v[64:67]
	v_mfma_f32_16x16x32_bf16 v[36:39], v[186:189], v[208:211], v[36:39]
	ds_read_b128 v[208:211], v191 offset:12288
	ds_read_b128 v[216:219], v96 offset:33792
	s_cbranch_vccnz .Lmy_k3_d3
	s_add_u32 m0, s12, 0x2000
	v_lshl_add_u64 v[220:221], v[152:153], 0, s[10:11]
	global_load_lds_dwordx4 v[220:221], off
	s_add_u32 m0, s12, 0x3000
	v_lshl_add_u64 v[220:221], v[152:153], 0, s[100:101]
	global_load_lds_dwordx4 v[220:221], off
.Lmy_k3_d3:
	s_waitcnt lgkmcnt(4)
	v_mfma_f32_16x16x32_bf16 v[88:91], v[130:133], v[212:215], v[88:91]
	v_mfma_f32_16x16x32_bf16 v[72:75], v[138:141], v[212:215], v[72:75]
	v_mfma_f32_16x16x32_bf16 v[52:55], v[182:185], v[212:215], v[52:55]
	v_mfma_f32_16x16x32_bf16 v[24:27], v[186:189], v[212:215], v[24:27]
	ds_read_b128 v[212:215], v191 offset:14336
	ds_read_b128 v[230:233], v96 offset:35840
	s_cbranch_vccnz .Lmy_k3_d4
	s_add_u32 m0, s12, 0xa000
	v_lshl_add_u64 v[220:221], v[160:161], 0, s[10:11]
	global_load_lds_dwordx4 v[220:221], off
	s_add_u32 m0, s12, 0xb000
	v_lshl_add_u64 v[220:221], v[160:161], 0, s[100:101]
	global_load_lds_dwordx4 v[220:221], off
.Lmy_k3_d4:
	s_waitcnt lgkmcnt(5)
	v_mfma_f32_16x16x32_bf16 v[80:83], v[130:133], v[134:137], v[80:83]
	v_mfma_f32_16x16x32_bf16 v[60:63], v[138:141], v[134:137], v[60:63]
	v_mfma_f32_16x16x32_bf16 v[40:43], v[182:185], v[134:137], v[40:43]
	v_mfma_f32_16x16x32_bf16 v[16:19], v[186:189], v[134:137], v[16:19]
	ds_read_b128 v[134:137], v191 offset:1024
	ds_read_b128 v[244:247], v96 offset:37888
	s_cbranch_vccnz .Lmy_k3_d5
	s_add_u32 m0, s12, 0x4000
	v_lshl_add_u64 v[220:221], v[154:155], 0, s[10:11]
	global_load_lds_dwordx4 v[220:221], off
	s_add_u32 m0, s12, 0x5000
	v_lshl_add_u64 v[220:221], v[154:155], 0, s[100:101]
	global_load_lds_dwordx4 v[220:221], off
.Lmy_k3_d5:
	s_waitcnt lgkmcnt(6)
	v_mfma_f32_16x16x32_bf16 v[68:71], v[130:133], v[204:207], v[68:71]
	v_mfma_f32_16x16x32_bf16 v[44:47], v[138:141], v[204:207], v[44:47]
	v_mfma_f32_16x16x32_bf16 v[28:31], v[182:185], v[204:207], v[28:31]
	v_mfma_f32_16x16x32_bf16 v[12:15], v[186:189], v[204:207], v[12:15]
	ds_read_b128 v[204:207], v191 offset:3072
	ds_read_b128 v[248:251], v96 offset:39936
	s_cbranch_vccnz .Lmy_k3_d6
	s_add_u32 m0, s12, 0xc000
	v_lshl_add_u64 v[220:221], v[162:163], 0, s[10:11]
	global_load_lds_dwordx4 v[220:221], off
	s_add_u32 m0, s12, 0xd000
	v_lshl_add_u64 v[220:221], v[162:163], 0, s[100:101]
	global_load_lds_dwordx4 v[220:221], off
.Lmy_k3_d6:
	s_waitcnt lgkmcnt(7)
	v_mfma_f32_16x16x32_bf16 v[56:59], v[130:133], v[208:211], v[56:59]
	v_mfma_f32_16x16x32_bf16 v[32:35], v[138:141], v[208:211], v[32:35]
	v_mfma_f32_16x16x32_bf16 v[20:23], v[182:185], v[208:211], v[20:23]
	v_mfma_f32_16x16x32_bf16 v[8:11], v[186:189], v[208:211], v[8:11]
	ds_read_b128 v[208:211], v191 offset:5120
	s_cbranch_vccnz .Lmy_k3_d7
	s_add_u32 m0, s12, 0x6000
	v_lshl_add_u64 v[220:221], v[156:157], 0, s[10:11]
	global_load_lds_dwordx4 v[220:221], off
	s_add_u32 m0, s12, 0x7000
	v_lshl_add_u64 v[220:221], v[156:157], 0, s[100:101]
	global_load_lds_dwordx4 v[220:221], off
; #define G_WAIT_V0() asm volatile("s_waitcnt vmcnt(0)" ::: "memory")
; __device__ __forceinline__ void g_kloop(const u16* __restrict__ Ab, const u16* __restrict__ Bb, const int K, char* smem, ...
;     ...
;   const int nt = K >> 6;
;   if (!pre) {
;     G_STAGE(0, 0);
;     G_WAIT_V0();
;     __syncthreads();
;   }
;   for (int t = 0; t < nt; ++t) {
;     const int cur = t & 1;
;     if (t + 1 < nt) G_STAGE(cur ^ 1, t + 1)
;     else if (has_next) {
;       char* sa_ = smem + wid * 1024;
;       char* sb_ = sa_ + G_TILE_B;
;       __builtin_amdgcn_global_load_lds((const unsigned*)(nA + o0), (unsigned*)(sa_), 16, 0, 0);
;       __builtin_amdgcn_global_load_lds((const unsigned*)(nB + o0), (unsigned*)(sb_), 16, 0, 0);
;       __builtin_amdgcn_global_load_lds((const unsigned*)(nA + o1), (unsigned*)(sa_ + 8192), 16, 0, 0);
;       __builtin_amdgcn_global_load_lds((const unsigned*)(nB + o1), (unsigned*)(sb_ + 8192), 16, 0, 0);
;       __builtin_amdgcn_global_load_lds((const unsigned*)(nA + o2), (unsigned*)(sa_ + 16384), 16, 0, 0);
;       __builtin_amdgcn_global_load_lds((const unsigned*)(nB + o2), (unsigned*)(sb_ + 16384), 16, 0, 0);
;       __builtin_amdgcn_global_load_lds((const unsigned*)(nA + o3), (unsigned*)(sa_ + 24576), 16, 0, 0);
;       __builtin_amdgcn_global_load_lds((const unsigned*)(nB + o3), (unsigned*)(sb_ + 24576), 16, 0, 0);
;     }
;     const char* sa = smem + cur * G_STAGE_B;
;     const char* sb = sa + G_TILE_B;
; #pragma unroll
;     for (int ks = 0; ks < 2; ++ks) {
;       s16x8 At[8], Bf[4];
; #pragma unroll
;       for (int m = 0; m < 8; ++m) At[m] = *(const s16x8*)(sa + g_lds_byte(wr * 128 + m * 16 + fr, ks * 32 + fq * 8));
; #pragma unroll
;       for (int n = 0; n < 4; ++n) Bf[n] = *(const s16x8*)(sb + g_lds_byte(wc * 64 + n * 16 + fr, ks * 32 + fq * 8));
; #pragma unroll
;       for (int m = 0; m < 8; ++m)
; #pragma unroll
;         for (int n = 0; n < 4; ++n)
;           acc[m][n] = __builtin_amdgcn_mfma_f32_16x16x32_bf16(__builtin_bit_cast(bf16x8, Bf[n]), __builtin_bit_cast(bf16x8, At[m]), acc[m][n], 0, 0, 0);
;     }
;     G_WAIT_V0();
;     __syncthreads();
;   }
.Lmy_k3_d7:
	s_waitcnt lgkmcnt(6)
	v_mfma_f32_16x16x32_bf16 v[122:125], v[130:133], v[212:215], v[122:125]
	v_mfma_f32_16x16x32_bf16 v[118:121], v[138:141], v[212:215], v[118:121]
	v_mfma_f32_16x16x32_bf16 v[126:129], v[182:185], v[212:215], v[126:129]
	v_mfma_f32_16x16x32_bf16 v[0:3], v[186:189], v[212:215], v[0:3]
	ds_read_b128 v[212:215], v191 offset:7168
	s_cbranch_vccnz .Lmy_k3_d8
	s_add_u32 m0, s12, 0xe000
	v_lshl_add_u64 v[220:221], v[164:165], 0, s[10:11]
	global_load_lds_dwordx4 v[220:221], off
	s_add_u32 m0, s12, 0xf000
	v_lshl_add_u64 v[220:221], v[164:165], 0, s[100:101]
	global_load_lds_dwordx4 v[220:221], off
.Lmy_k3_d8:
	s_waitcnt lgkmcnt(5)
	v_mfma_f32_16x16x32_bf16 v[4:7], v[216:219], v[134:137], v[4:7]
	v_mfma_f32_16x16x32_bf16 v[114:117], v[230:233], v[134:137], v[114:117]
	s_waitcnt lgkmcnt(4)
	v_mfma_f32_16x16x32_bf16 v[110:113], v[244:247], v[134:137], v[110:113]
	s_waitcnt lgkmcnt(2)
	v_mfma_f32_16x16x32_bf16 v[106:109], v[248:251], v[134:137], v[106:109]
	ds_read_b128 v[134:137], v191 offset:9216
	v_mfma_f32_16x16x32_bf16 v[102:105], v[216:219], v[204:207], v[102:105]
	v_mfma_f32_16x16x32_bf16 v[92:95], v[230:233], v[204:207], v[92:95]
	v_mfma_f32_16x16x32_bf16 v[76:79], v[244:247], v[204:207], v[76:79]
	v_mfma_f32_16x16x32_bf16 v[48:51], v[248:251], v[204:207], v[48:51]
	ds_read_b128 v[204:207], v191 offset:11264
	s_waitcnt lgkmcnt(3)
	v_mfma_f32_16x16x32_bf16 v[98:101], v[216:219], v[208:211], v[98:101]
	v_mfma_f32_16x16x32_bf16 v[84:87], v[230:233], v[208:211], v[84:87]
	v_mfma_f32_16x16x32_bf16 v[64:67], v[244:247], v[208:211], v[64:67]
	v_mfma_f32_16x16x32_bf16 v[36:39], v[248:251], v[208:211], v[36:39]
	ds_read_b128 v[208:211], v191 offset:13312
	s_waitcnt lgkmcnt(3)
	v_mfma_f32_16x16x32_bf16 v[88:91], v[216:219], v[212:215], v[88:91]
	v_mfma_f32_16x16x32_bf16 v[72:75], v[230:233], v[212:215], v[72:75]
	v_mfma_f32_16x16x32_bf16 v[52:55], v[244:247], v[212:215], v[52:55]
	v_mfma_f32_16x16x32_bf16 v[24:27], v[248:251], v[212:215], v[24:27]
	ds_read_b128 v[212:215], v191 offset:15360
	s_waitcnt lgkmcnt(3)
	v_mfma_f32_16x16x32_bf16 v[80:83], v[216:219], v[134:137], v[80:83]
	v_mfma_f32_16x16x32_bf16 v[60:63], v[230:233], v[134:137], v[60:63]
	v_mfma_f32_16x16x32_bf16 v[40:43], v[244:247], v[134:137], v[40:43]
	v_mfma_f32_16x16x32_bf16 v[16:19], v[248:251], v[134:137], v[16:19]
	s_waitcnt lgkmcnt(2)
	v_mfma_f32_16x16x32_bf16 v[68:71], v[216:219], v[204:207], v[68:71]
	v_mfma_f32_16x16x32_bf16 v[44:47], v[230:233], v[204:207], v[44:47]
	v_mfma_f32_16x16x32_bf16 v[28:31], v[244:247], v[204:207], v[28:31]
	v_mfma_f32_16x16x32_bf16 v[12:15], v[248:251], v[204:207], v[12:15]
	s_waitcnt vmcnt(0)
	s_waitcnt vmcnt(0) lgkmcnt(0)
	s_barrier
	s_add_i32 s7, s7, 0x10000
	s_add_u32 s10, s10, 0x80
	s_addc_u32 s11, s11, 0
	s_and_b32 s13, s7, 0x10000
	v_or_b32_e32 v96, s13, v179
	v_add_u32_e32 v191, v96, v180
	v_add_u32_e32 v96, v96, v181
	ds_read_b128 v[130:133], v96 offset:32768
	ds_read_b128 v[138:141], v96 offset:34816
	ds_read_b128 v[182:185], v96 offset:36864
	ds_read_b128 v[186:189], v96 offset:38912
	ds_read_b128 v[134:137], v191
	ds_read_b128 v[204:207], v191 offset:2048
	v_mfma_f32_16x16x32_bf16 v[56:59], v[216:219], v[208:211], v[56:59]
	v_mfma_f32_16x16x32_bf16 v[32:35], v[230:233], v[208:211], v[32:35]
	v_mfma_f32_16x16x32_bf16 v[20:23], v[244:247], v[208:211], v[20:23]
	v_mfma_f32_16x16x32_bf16 v[8:11], v[248:251], v[208:211], v[8:11]
	ds_read_b128 v[208:211], v191 offset:4096
	v_mfma_f32_16x16x32_bf16 v[122:125], v[216:219], v[212:215], v[122:125]
	v_mfma_f32_16x16x32_bf16 v[118:121], v[230:233], v[212:215], v[118:121]
	v_mfma_f32_16x16x32_bf16 v[126:129], v[244:247], v[212:215], v[126:129]
	v_mfma_f32_16x16x32_bf16 v[0:3], v[248:251], v[212:215], v[0:3]
	ds_read_b128 v[212:215], v191 offset:6144
	s_cmpk_lg_i32 s10, 0x780
	s_cbranch_scc1 .Lmy_k3_top
	s_waitcnt lgkmcnt(0)
	s_andn2_b64 vcc, exec, s[8:9]
	s_cbranch_vccnz .LBB0_625
	s_lshl_b32 s8, s19, 8
	s_ashr_i32 s9, s8, 31
	s_lshl_b64 s[8:9], s[8:9], 11
	s_add_u32 s8, s86, s8
	s_addc_u32 s9, s87, s9
	s_lshl_b32 s10, s18, 8
	s_ashr_i32 s11, s10, 31
	s_lshl_b64 s[10:11], s[10:11], 11
	s_add_u32 s10, s14, s10
	v_lshlrev_b64 v[130:131], 1, v[142:143]
	v_add_u32_e32 v151, 0x8000, v166
	v_readfirstlane_b32 s7, v166
	s_addc_u32 s11, s15, s11
	v_lshl_add_u64 v[132:133], s[8:9], 0, v[130:131]
	v_add_u32_e32 v150, 0x2000, v166
	s_mov_b32 m0, s7
	v_readfirstlane_b32 s7, v151
	v_lshl_add_u64 v[130:131], s[10:11], 0, v[130:131]
	v_lshlrev_b64 v[134:135], 1, v[144:145]
	v_lshlrev_b64 v[142:143], 1, v[148:149]
	v_add_u32_e32 v149, 0xa000, v166
	global_load_lds_dwordx4 v[132:133], off
	s_mov_b32 m0, s7
	v_readfirstlane_b32 s7, v150
	v_lshl_add_u64 v[136:137], s[8:9], 0, v[134:135]
	v_add_u32_e32 v148, 0x4000, v166
	global_load_lds_dwordx4 v[130:131], off
	s_mov_b32 m0, s7
	v_readfirstlane_b32 s7, v149
	v_lshl_add_u64 v[134:135], s[10:11], 0, v[134:135]
	v_lshlrev_b64 v[138:139], 1, v[146:147]
	v_add_u32_e32 v147, 0xc000, v166
	global_load_lds_dwordx4 v[136:137], off
	s_mov_b32 m0, s7
	v_readfirstlane_b32 s7, v148
	v_lshl_add_u64 v[140:141], s[8:9], 0, v[138:139]
	v_add_u32_e32 v146, 0x6000, v166
	global_load_lds_dwordx4 v[134:135], off
	s_mov_b32 m0, s7
	v_readfirstlane_b32 s7, v147
	v_lshl_add_u64 v[138:139], s[10:11], 0, v[138:139]
	v_add_u32_e32 v96, 0xe000, v166
	global_load_lds_dwordx4 v[140:141], off
	s_mov_b32 m0, s7
	v_readfirstlane_b32 s7, v146
	v_lshl_add_u64 v[144:145], s[8:9], 0, v[142:143]
	global_load_lds_dwordx4 v[138:139], off
	s_mov_b32 m0, s7
	v_readfirstlane_b32 s7, v96
	v_lshl_add_u64 v[142:143], s[10:11], 0, v[142:143]
	global_load_lds_dwordx4 v[144:145], off
	s_mov_b32 m0, s7
	s_nop 0
	global_load_lds_dwordx4 v[142:143], off
	s_branch .LBB0_625

; __global__ void __launch_bounds__(NTHREADS, 2) mega_kernel(Params P) {
;   __shared__ __attribute__((aligned(1024))) char smem[163840];
	.amdhsa_kernel _Z11mega_kernel6Params
		.amdhsa_group_segment_fixed_size 163840
		.amdhsa_private_segment_fixed_size 0
		.amdhsa_kernarg_size 568
		.amdhsa_user_sgpr_count 2
		.amdhsa_user_sgpr_dispatch_ptr 0
		.amdhsa_user_sgpr_queue_ptr 0
		.amdhsa_user_sgpr_kernarg_segment_ptr 1
		.amdhsa_user_sgpr_dispatch_id 0
		.amdhsa_user_sgpr_kernarg_preload_length 0
		.amdhsa_user_sgpr_kernarg_preload_offset 0
		.amdhsa_user_sgpr_private_segment_size 0
		.amdhsa_uses_dynamic_stack 0
		.amdhsa_enable_private_segment 0
		.amdhsa_system_sgpr_workgroup_id_x 1
		.amdhsa_system_sgpr_workgroup_id_y 0
		.amdhsa_system_sgpr_workgroup_id_z 0
		.amdhsa_system_sgpr_workgroup_info 0
		.amdhsa_system_vgpr_workitem_id 2
		.amdhsa_next_free_vgpr 256
		.amdhsa_next_free_sgpr 102
		.amdhsa_accum_offset 256
		.amdhsa_reserve_vcc 1
		.amdhsa_float_round_mode_32 0
		.amdhsa_float_round_mode_16_64 0
		.amdhsa_float_denorm_mode_32 3
		.amdhsa_float_denorm_mode_16_64 3
		.amdhsa_dx10_clamp 1
		.amdhsa_ieee_mode 1
		.amdhsa_fp16_overflow 0
		.amdhsa_tg_split 0
		.amdhsa_exception_fp_ieee_invalid_op 0
		.amdhsa_exception_fp_denorm_src 0
		.amdhsa_exception_fp_ieee_div_zero 0
		.amdhsa_exception_fp_ieee_overflow 0
		.amdhsa_exception_fp_ieee_underflow 0
		.amdhsa_exception_fp_ieee_inexact 0
		.amdhsa_exception_int_div_zero 0
	.end_amdhsa_kernel
